# speedup vs baseline: 1.0173x; 1.0052x over previous
; __device__ __forceinline__ uint4 ldg16(const void* p) { const u32x4 v = *(const __attribute__((address_space(1))) u32x4*)(p); return make_uint4(v.x, v.y, v.z, v.w); }
; __device__ __forceinline__ void attn_phase(const Params& p, char* shmc, int tid, int wv) {
;   u16* Qs = (u16*)shmc;
;   u16* Ks = Qs + 64 * 136;
;   u16* Vt = Ks + 64 * 136;
;   float* Zs = (float*)(Vt + 128 * 72);
;   u16* Ps = (u16*)(Zs + 64 * 68);
;   const u16* QKV = (const u16*)(p.ws + O_QKV1 * MiB);
;   u16* AO = (u16*)(p.ws + O_AO * MiB);
;   const int lane = tid & 63, r = lane & 15, quad = lane >> 4;
;   const int mt = wv & 3;
;   for (int tile = blockIdx.x; tile < 4096; tile += gridDim.x) {
;     const int h = tile & 15, qb = 255 - (tile >> 4);
;     {
;       const int row = tid >> 3, c0 = (tid & 7) * 16;
;       const u16* src = QKV + ((long)qb * 64 + row) * 6144 + h * 128 + c0;
;       *(uint4*)&Qs[row * 136 + c0] = ldg16(src);
;       *(uint4*)&Qs[row * 136 + c0 + 8] = ldg16(src + 8);
;     }
;     float carry = 0.f;
;     f32x4 oacc[4];
; #pragma unroll
;     for (int i = 0; i < 4; ++i) oacc[i] = f32x4{0.f, 0.f, 0.f, 0.f};
;     const int krow = tid >> 3, kc0 = (tid & 7) * 16, vkey = tid & 63, vd0 = wv * 16;
;     uint4 ka, kb4, va, vb;
;     {
;       const u16* src = QKV + ((long)qb * 64 + krow) * 6144 + 2048 + h * 128 + kc0;
;       ka = ldg16(src); kb4 = ldg16(src + 8);
;       const u16* vs = QKV + ((long)qb * 64 + vkey) * 6144 + 4096 + h * 128 + vd0;
;       va = ldg16(vs); vb = ldg16(vs + 8);
;     }
; __global__ __launch_bounds__(512) void mk(Params p_arg, int ph0, int ph1) {
;     ...
;     if (ph == 11) attn_phase(p, shmc, tid, wv);
.LBB0_302:
	s_cmp_lt_i32 s3, 4
	s_mov_b64 s[8:9], -1
	s_cbranch_scc1 .LBB0_341
	s_cmp_lt_i32 s3, 11
	s_cbranch_scc1 .LBB0_334
	s_cmp_eq_u32 s3, 11
	s_cbranch_scc0 .LBB0_333
	v_readlane_b32 s8, v253, 14
	v_readlane_b32 s9, v253, 15
	s_andn2_b64 vcc, exec, s[8:9]
	s_cbranch_vccnz .LBB0_333
	v_mov_b64_e32 v[0:1], s[62:63]
	flat_load_dwordx2 v[2:3], v[0:1] offset:136
	v_and_b32_e32 v6, 7, v214
	s_mov_b64 s[8:9], 0x8000000
	v_and_b32_e32 v1, 15, v214
	v_ashrrev_i32_e32 v44, 3, v214
	v_lshlrev_b32_e32 v0, 4, v6
	s_movk_i32 s7, 0x88
	v_lshlrev_b32_e32 v10, 5, v6
	v_lshrrev_b32_e32 v8, 2, v214
	s_movk_i32 s14, 0x90
	v_and_b32_e32 v42, 63, v214
	v_lshlrev_b32_e32 v212, 1, v1
	s_mov_b64 s[10:11], 0x14000000
	v_mov_b32_e32 v12, 0x3fc7
	v_ashrrev_i32_e32 v45, 31, v44
	v_cmp_gt_u32_e64 s[12:13], 4, v6
	v_lshl_or_b32 v81, v6, 3, v12
	v_lshlrev_b32_e32 v56, 1, v0
	s_waitcnt vmcnt(0) lgkmcnt(0)
	v_lshl_add_u64 v[40:41], v[2:3], 0, s[8:9]
	v_mad_u64_u32 v[4:5], s[8:9], v44, s7, v[0:1]
	s_movk_i32 s8, 0x110
	v_readlane_b32 s7, v253, 35
	v_and_b32_e32 v5, 48, v214
	v_mul_lo_u32 v9, v44, s8
	v_lshl_add_u32 v43, v4, 1, v236
	v_or_b32_e32 v4, s7, v1
	v_add_u32_e32 v7, 0x110, v5
	v_add3_u32 v51, s8, v9, v10
	v_lshlrev_b32_e32 v9, 2, v214
	v_mad_u32_u24 v47, v4, s8, v7
	v_and_or_b32 v46, v8, 12, s7
	v_and_b32_e32 v53, 0xe0, v9
	v_mul_lo_u32 v9, v44, s14
	v_readlane_b32 s7, v254, 12
	v_mul_u32_u24_e32 v4, 0x90, v4
	v_lshl_add_u64 v[2:3], v[2:3], 0, v[212:213]
	v_add3_u32 v55, s7, v9, v0
	v_add3_u32 v76, s7, v4, v5
	v_readlane_b32 s7, v253, 36
	v_lshl_add_u64 v[48:49], v[2:3], 0, s[10:11]
	v_lshl_add_u32 v8, v1, 2, v236
	v_readlane_b32 s7, v253, 37
	v_lshlrev_b32_e32 v9, 2, v42
	v_add_u32_e32 v78, 4, v9
	v_or_b32_e32 v2, s7, v1
	v_readlane_b32 s7, v253, 39
	v_add_u32_e32 v79, 8, v9
	v_add_u32_e32 v80, 16, v9
	v_or_b32_e32 v3, s7, v1
	v_readlane_b32 s7, v253, 38
	v_mul_lo_u32 v2, v2, s8
	v_mul_lo_u32 v3, v3, s8
	v_add_u32_e32 v4, s7, v8
	v_readlane_b32 s7, v253, 40
	v_mul_u32_u24_e32 v5, 0x110, v46
	v_or_b32_e32 v50, 1, v46
	v_add_u32_e32 v8, s7, v8
	v_readlane_b32 s7, v254, 33
	v_or_b32_e32 v52, 2, v46
	v_or_b32_e32 v54, 3, v46
	v_or_b32_e32 v9, s7, v1
	v_readlane_b32 s7, v253, 41
	v_mul_lo_u32 v9, v9, s14
	v_cmp_eq_u32_e64 s[8:9], 7, v6
	v_or_b32_e32 v10, s7, v1
	v_readlane_b32 s7, v253, 42
	v_mul_lo_u32 v10, v10, s14
	v_cmp_gt_u32_e64 s[10:11], 6, v6
	v_or_b32_e32 v11, s7, v1
	v_readlane_b32 s7, v254, 34
	v_mul_lo_u32 v11, v11, s14
	v_add_u32_e32 v82, v7, v2
	v_or_b32_e32 v1, s7, v1
	v_mul_lo_u32 v1, v1, s14
	v_add_u32_e32 v83, v7, v3
	v_add_u32_e32 v84, v4, v5
	v_add_u32_e32 v85, v8, v5
	v_bfe_u32 v2, v214, 4, 2
	v_bfe_u32 v3, v214, 2, 2
	v_lshl_add_u32 v2, v2, 3, v3
	v_mul_u32_u24_e32 v2, 0x110, v2
	v_and_b32_e32 v3, 3, v214
	v_lshl_add_u32 v2, v3, 3, v2
	v_lshrrev_b32_e32 v3, 8, v214
	v_lshl_add_u32 v2, v3, 7, v2
	v_add_u32_e32 v86, 0x110, v2
	v_lshrrev_b32_e32 v3, 6, v214
	v_lshlrev_b32_e32 v3, 5, v3
	v_mul_u32_u24_e32 v2, 0x110, v42
	v_add_u32_e32 v2, 0x110, v2
	v_add_u32_e32 v77, v2, v3
	s_mov_b32 s7, s2
	s_branch .LBB0_308

; __device__ __forceinline__ uint4 ldg16(const void* p) { const u32x4 v = *(const __attribute__((address_space(1))) u32x4*)(p); return make_uint4(v.x, v.y, v.z, v.w); }
; __device__ __forceinline__ void attn_phase(const Params& p, char* shmc, int tid, int wv) {
;     ...
;       {
;         *(uint4*)&Ks[krow * 136 + kc0] = ka;
;         *(uint4*)&Ks[krow * 136 + kc0 + 8] = kb4;
;         const unsigned vw[8] = {va.x, va.y, va.z, va.w, vb.x, vb.y, vb.z, vb.w};
; #pragma unroll
;         for (int i = 0; i < 8; ++i) { Vt[(vd0 + 2 * i) * 72 + vkey] = (u16)(vw[i] & 0xffffu); Vt[(vd0 + 2 * i + 1) * 72 + vkey] = (u16)(vw[i] >> 16); }
;       }
;       __syncthreads();
;       {
;         const int kn = kb > 0 ? kb - 1 : 0;
;         const u16* src = QKV + ((long)kn * 64 + krow) * 6144 + 2048 + h * 128 + kc0;
;         ka = ldg16(src); kb4 = ldg16(src + 8);
;         const u16* vs = QKV + ((long)kn * 64 + vkey) * 6144 + 4096 + h * 128 + vd0;
;         va = ldg16(vs); vb = ldg16(vs + 8);
;       }
;       {
;         const int ntb = (wv >> 2) * 2;
;         f32x4 z[2] = {{0.f, 0.f, 0.f, 0.f}, {0.f, 0.f, 0.f, 0.f}};
; #pragma unroll
;         for (int kk = 0; kk < 4; ++kk) {
;           const bf16x8 a = *(const bf16x8*)&Qs[(16 * mt + r) * 136 + kk * 32 + quad * 8];
; #pragma unroll
;           for (int i = 0; i < 2; ++i) {
;             const bf16x8 b = *(const bf16x8*)&Ks[(16 * (ntb + i) + r) * 136 + kk * 32 + quad * 8];
;             z[i] = __builtin_amdgcn_mfma_f32_16x16x32_bf16(a, b, z[i], 0, 0, 0);
;           }
;         }
; #pragma unroll
;         for (int i = 0; i < 2; ++i)
; #pragma unroll
;           for (int j = 0; j < 4; ++j) Zs[(16 * mt + 4 * quad + j) * 68 + 16 * (ntb + i) + r] = z[i][j] * 0.08838834764831845f;
;       }
;       __syncthreads();
;       {
;         const int row = tid >> 3, part = tid & 7;
;         const float4 za = *(const float4*)&Zs[row * 68 + part * 8], zb = *(const float4*)&Zs[row * 68 + part * 8 + 4];
;         const float z[8] = {za.x, za.y, za.z, za.w, zb.x, zb.y, zb.z, zb.w};
;         const int qpos = qb * 64 + row, kpos0 = kb * 64 + part * 8;
;         float sp[8];
;         float ptot = 0.f;
; #pragma unroll
;         for (int i = 0; i < 8; ++i) {
;           const bool valid = (kpos0 + i) < qpos;
;           sp[i] = valid ? (fmaxf(z[i], 0.f) + __logf(1.f + __expf(-fabsf(z[i])))) : 0.f;
.LBB0_311:
	v_sub_u32_e64 v212, s68, 2 clamp
	s_waitcnt vmcnt(5)
	ds_write_b128 v43, v[8:11] offset:17408
	s_waitcnt vmcnt(4)
	ds_write_b128 v43, v[12:15] offset:17424
	ds_write_b128 v77, v[4:7] offset:34816
	ds_write_b128 v77, v[0:3] offset:34832
	v_lshlrev_b64 v[0:1], 6, v[212:213]
	v_lshl_add_u64 v[2:3], v[0:1], 0, v[44:45]
	v_mad_u64_u32 v[4:5], s[14:15], v2, s71, v[40:41]
	v_mad_i32_i24 v5, v3, s71, v5
	s_lshl_b32 s88, s59, 1
	v_lshl_add_u64 v[2:3], v[4:5], 0, s[88:89]
	v_lshl_add_u64 v[2:3], v[2:3], 0, v[56:57]
	v_lshl_add_u64 v[4:5], v[2:3], 0, s[54:55]
	v_add_co_u32_e32 v2, vcc, s66, v2
	v_or_b32_e32 v0, v0, v42
	s_nop 0
	v_addc_co_u32_e32 v3, vcc, 0, v3, vcc
	s_waitcnt lgkmcnt(0)
	s_barrier
	global_load_dwordx4 v[8:11], v[2:3], off
	global_load_dwordx4 v[12:15], v[4:5], off offset:16
	v_mad_u64_u32 v[2:3], s[14:15], v0, s71, v[40:41]
	v_mad_u32_u24 v3, v1, s71, v3
	v_lshl_add_u64 v[0:1], v[2:3], 0, s[88:89]
	v_lshl_add_u64 v[0:1], v[0:1], 0, s[36:37]
	v_lshl_add_u64 v[2:3], v[0:1], 0, s[46:47]
	v_add_co_u32_e32 v0, vcc, s67, v0
	v_add_u32_e32 v58, 0xd000, v84
	s_nop 0
	v_addc_co_u32_e32 v1, vcc, 0, v1, vcc
	global_load_dwordx4 v[4:7], v[0:1], off
	s_nop 0
	global_load_dwordx4 v[0:3], v[2:3], off offset:16
	ds_read_b128 v[96:99], v47
	ds_read_b128 v[112:115], v82 offset:17408
	ds_read_b128 v[128:131], v83 offset:17408
	ds_read_b128 v[100:103], v47 offset:64
	ds_read_b128 v[116:119], v82 offset:17472
	ds_read_b128 v[132:135], v83 offset:17472
	ds_read_b128 v[104:107], v47 offset:128
	ds_read_b128 v[120:123], v82 offset:17536
	ds_read_b128 v[136:139], v83 offset:17536
	ds_read_b128 v[108:111], v47 offset:192
	ds_read_b128 v[124:127], v82 offset:17600
	ds_read_b128 v[140:143], v83 offset:17600
	s_waitcnt lgkmcnt(10)
	v_mfma_f32_16x16x32_bf16 v[36:39], v[96:99], v[112:115], 0
	s_waitcnt lgkmcnt(9)
	v_mfma_f32_16x16x32_bf16 v[32:35], v[96:99], v[128:131], 0
	s_waitcnt lgkmcnt(7)
	v_mfma_f32_16x16x32_bf16 v[36:39], v[100:103], v[116:119], v[36:39]
	s_waitcnt lgkmcnt(6)
	v_mfma_f32_16x16x32_bf16 v[32:35], v[100:103], v[132:135], v[32:35]
	s_waitcnt lgkmcnt(4)
	v_mfma_f32_16x16x32_bf16 v[36:39], v[104:107], v[120:123], v[36:39]
	s_waitcnt lgkmcnt(3)
	v_mfma_f32_16x16x32_bf16 v[32:35], v[104:107], v[136:139], v[32:35]
	s_waitcnt lgkmcnt(1)
	v_mfma_f32_16x16x32_bf16 v[36:39], v[108:111], v[124:127], v[36:39]
	s_waitcnt lgkmcnt(0)
	v_mfma_f32_16x16x32_bf16 v[32:35], v[108:111], v[140:143], v[32:35]
	s_nop 7
	v_mul_f32_e32 v36, 0x3db504f3, v36
	v_mul_f32_e32 v37, 0x3db504f3, v37
	ds_write2_b32 v58, v36, v37 offset1:68
	v_mul_f32_e32 v36, 0x3db504f3, v38
	v_mul_f32_e32 v37, 0x3db504f3, v39
	ds_write2_b32 v58, v36, v37 offset0:136 offset1:204
	v_mul_f32_e32 v32, 0x3db504f3, v32
	v_mul_f32_e32 v33, 0x3db504f3, v33
	v_add_u32_e32 v36, 0xd000, v85
	ds_write2_b32 v36, v32, v33 offset1:68
	v_mul_f32_e32 v32, 0x3db504f3, v34
	v_mul_f32_e32 v33, 0x3db504f3, v35
	ds_write2_b32 v36, v32, v33 offset0:136 offset1:204
	s_waitcnt lgkmcnt(0)
	s_barrier
	ds_read_b128 v[32:35], v51 offset:53248
	ds_read_b128 v[36:39], v51 offset:53264
	v_add_u32_e32 v58, -7, v91
	v_cmp_lt_i32_e32 vcc, v58, v90
	v_add_u32_e32 v58, -6, v91
	v_cmp_lt_i32_e64 s[14:15], v58, v90
	v_add_u32_e32 v58, -5, v91
	v_cmp_lt_i32_e64 s[16:17], v58, v90
	v_add_u32_e32 v58, -4, v91
	v_cmp_lt_i32_e64 s[18:19], v58, v90
	v_add_u32_e32 v58, -3, v91
	v_cmp_lt_i32_e64 s[20:21], v58, v90
	v_add_u32_e32 v58, -2, v91
	v_cmp_lt_i32_e64 s[22:23], v58, v90
	v_add_u32_e32 v58, -1, v91
	v_cmp_lt_i32_e64 s[24:25], v58, v90
	v_cmp_lt_i32_e64 s[26:27], v91, v90
	s_waitcnt lgkmcnt(0)
	v_mul_f32_e64 v96, |v32|, s74
	v_mul_f32_e64 v97, |v33|, s74
	v_mul_f32_e64 v98, |v34|, s74
	v_mul_f32_e64 v99, |v35|, s74
	v_mul_f32_e64 v100, |v36|, s74
	v_mul_f32_e64 v101, |v37|, s74
	v_mul_f32_e64 v102, |v38|, s74
	v_mul_f32_e64 v103, |v39|, s74
	v_exp_f32_e32 v96, v96
	v_exp_f32_e32 v97, v97
	v_exp_f32_e32 v98, v98
	v_exp_f32_e32 v99, v99
	v_exp_f32_e32 v100, v100
	v_exp_f32_e32 v101, v101
	v_exp_f32_e32 v102, v102
	v_exp_f32_e32 v103, v103
	v_max_f32_e32 v60, v32, v32
	v_max_f32_e32 v62, v33, v33
	v_max_f32_e32 v64, v34, v34
	v_max_f32_e32 v66, v35, v35
	v_max_f32_e32 v68, v36, v36
	v_max_f32_e32 v70, v37, v37
	v_max_f32_e32 v72, v38, v38
	v_max_f32_e32 v74, v39, v39
	v_add_f32_e32 v96, 1.0, v96
	v_add_f32_e32 v97, 1.0, v97
	v_add_f32_e32 v98, 1.0, v98
	v_add_f32_e32 v99, 1.0, v99
	v_add_f32_e32 v100, 1.0, v100
	v_add_f32_e32 v101, 1.0, v101
	v_add_f32_e32 v102, 1.0, v102
	v_add_f32_e32 v103, 1.0, v103
	v_log_f32_e32 v96, v96
	v_log_f32_e32 v97, v97
	v_log_f32_e32 v98, v98
	v_log_f32_e32 v99, v99
	v_log_f32_e32 v100, v100
	v_log_f32_e32 v101, v101
	v_log_f32_e32 v102, v102
	v_log_f32_e32 v103, v103
	v_max_f32_e32 v60, 0, v60
	v_max_f32_e32 v62, 0, v62
	v_max_f32_e32 v64, 0, v64
	v_max_f32_e32 v66, 0, v66
	v_max_f32_e32 v68, 0, v68
	v_max_f32_e32 v70, 0, v70
	v_max_f32_e32 v72, 0, v72
	v_max_f32_e32 v74, 0, v74
	v_mul_f32_e32 v104, 0x3f317217, v96
	v_mul_f32_e32 v105, 0x3f317217, v97
	v_mul_f32_e32 v106, 0x3f317217, v98
	v_mul_f32_e32 v107, 0x3f317217, v99
	v_mul_f32_e32 v108, 0x3f317217, v100
	v_mul_f32_e32 v109, 0x3f317217, v101
	v_mul_f32_e32 v110, 0x3f317217, v102
	v_mul_f32_e32 v111, 0x3f317217, v103
	v_fma_f32 v104, v96, s75, -v104
	v_fma_f32 v105, v97, s75, -v105
	v_fma_f32 v106, v98, s75, -v106
	v_fma_f32 v107, v99, s75, -v107
	v_fma_f32 v108, v100, s75, -v108
	v_fma_f32 v109, v101, s75, -v109
	v_fma_f32 v110, v102, s75, -v110
	v_fma_f32 v111, v103, s75, -v111
	v_fmac_f32_e32 v104, 0x3377d1cf, v96
	v_fmac_f32_e32 v105, 0x3377d1cf, v97
	v_fmac_f32_e32 v106, 0x3377d1cf, v98
	v_fmac_f32_e32 v107, 0x3377d1cf, v99
	v_fmac_f32_e32 v108, 0x3377d1cf, v100
	v_fmac_f32_e32 v109, 0x3377d1cf, v101
	v_fmac_f32_e32 v110, 0x3377d1cf, v102
	v_fmac_f32_e32 v111, 0x3377d1cf, v103
	v_fmac_f32_e32 v104, 0x3f317217, v96
	v_fmac_f32_e32 v105, 0x3f317217, v97
	v_fmac_f32_e32 v106, 0x3f317217, v98
	v_fmac_f32_e32 v107, 0x3f317217, v99
	v_fmac_f32_e32 v108, 0x3f317217, v100
	v_fmac_f32_e32 v109, 0x3f317217, v101
	v_fmac_f32_e32 v110, 0x3f317217, v102
	v_fmac_f32_e32 v111, 0x3f317217, v103
	v_add_f32_e32 v60, v60, v104
	v_add_f32_e32 v62, v62, v105
	v_add_f32_e32 v64, v64, v106
	v_add_f32_e32 v66, v66, v107
	v_add_f32_e32 v68, v68, v108
	v_add_f32_e32 v70, v70, v109
	v_add_f32_e32 v72, v72, v110
	v_add_f32_e32 v74, v74, v111
	v_cndmask_b32_e32 v60, 0, v60, vcc
	v_cndmask_b32_e64 v62, 0, v62, s[14:15]
	v_cndmask_b32_e64 v64, 0, v64, s[16:17]
	v_cndmask_b32_e64 v66, 0, v66, s[18:19]
	v_cndmask_b32_e64 v68, 0, v68, s[20:21]
	v_cndmask_b32_e64 v70, 0, v70, s[22:23]
	v_cndmask_b32_e64 v72, 0, v72, s[24:25]
	v_cndmask_b32_e64 v74, 0, v74, s[26:27]
	v_add_f32_e32 v58, 0, v60
	v_add_f32_e32 v58, v58, v62
	v_add_f32_e32 v58, v58, v64
	v_add_f32_e32 v58, v58, v66
	v_add_f32_e32 v58, v58, v68
	v_add_f32_e32 v58, v58, v70
	v_add_f32_e32 v58, v58, v72
	v_add_f32_e32 v58, v58, v74
	ds_bpermute_b32 v61, v78, v58
	v_mov_b32_e32 v73, v74
	v_mov_b32_e32 v71, v72
	v_mov_b32_e32 v69, v70
	v_mov_b32_e32 v67, v68
	s_waitcnt lgkmcnt(0)
; __device__ __forceinline__ unsigned pack2(float a, float b) { const f32v2_ v = {a, b}; const bf16v2_ r = __builtin_convertvector(v, bf16v2_); return __builtin_bit_cast(unsigned, r); }
; __device__ __forceinline__ float shfl_idx(float v, int srclane) { return __int_as_float(__builtin_amdgcn_ds_bpermute(srclane << 2, __float_as_int(v))); }
; __device__ __forceinline__ void attn_phase(const Params& p, char* shmc, int tid, int wv) {
;     ...
;         const int row = tid >> 3, part = tid & 7;
;         const float4 za = *(const float4*)&Zs[row * 68 + part * 8], zb = *(const float4*)&Zs[row * 68 + part * 8 + 4];
;         const float z[8] = {za.x, za.y, za.z, za.w, zb.x, zb.y, zb.z, zb.w};
;         const int qpos = qb * 64 + row, kpos0 = kb * 64 + part * 8;
;         float sp[8];
;         float ptot = 0.f;
; #pragma unroll
;         for (int i = 0; i < 8; ++i) {
;           const bool valid = (kpos0 + i) < qpos;
;           sp[i] = valid ? (fmaxf(z[i], 0.f) + __logf(1.f + __expf(-fabsf(z[i])))) : 0.f;
;           ptot += sp[i];
;         }
;         float tot = ptot;
; #pragma unroll
;         for (int o = 1; o < 8; o <<= 1) { const float v = shfl_idx(tot, lane + o); if (part + o < 8) tot += v; }
;         float running = carry - (tot - ptot);
;         float a[8];
; #pragma unroll
;         for (int i = 7; i >= 0; --i) {
;           const bool valid = (kpos0 + i) < qpos;
;           a[i] = valid ? __expf(z[i] - sp[i] + running) : 0.f;
;           running -= sp[i];
;         }
;         const float all = shfl_idx(tot, lane & ~7);
;         carry -= all;
;         *(uint4*)&Ps[row * 72 + part * 8] = make_uint4(pack2(a[0], a[1]), pack2(a[2], a[3]), pack2(a[4], a[5]), pack2(a[6], a[7]));
;       }
;       __syncthreads();
;       {
;         const int ntb = (wv >> 2) * 4;
; #pragma unroll
;         for (int kk = 0; kk < 2; ++kk) {
;           const bf16x8 a = *(const bf16x8*)&Ps[(16 * mt + r) * 72 + kk * 32 + quad * 8];
; #pragma unroll
;           for (int i = 0; i < 4; ++i) {
;             const bf16x8 b = *(const bf16x8*)&Vt[(16 * (ntb + i) + r) * 72 + kk * 32 + quad * 8];
;             oacc[i] = __builtin_amdgcn_mfma_f32_16x16x32_bf16(a, b, oacc[i], 0, 0, 0);
;           }
;         }
;       }
;       const int more = __syncthreads_or(carry > -120.f);
;       if (!more) break;
	v_add_f32_e32 v61, v58, v61
	v_cndmask_b32_e64 v61, v61, v58, s[8:9]
	ds_bpermute_b32 v63, v79, v61
	v_mov_b32_e32 v65, v66
	s_bitcmp1_b32 exec_hi, 0
	s_waitcnt lgkmcnt(0)
	v_add_f32_e32 v63, v61, v63
	v_cndmask_b32_e64 v61, v61, v63, s[10:11]
	ds_bpermute_b32 v63, v80, v61
	s_waitcnt lgkmcnt(0)
	v_add_f32_e32 v63, v61, v63
	v_cndmask_b32_e64 v94, v61, v63, s[12:13]
	v_sub_f32_e32 v75, v94, v58
	v_mov_b32_e32 v58, v39
	v_pk_add_f32 v[92:93], v[58:59], v[74:75] neg_lo:[0,1] neg_hi:[0,1]
	v_mov_b32_e32 v63, v64
	v_add_f32_e32 v39, v92, v93
	v_mul_f32_e32 v39, 0x3fb8aa3b, v39
	v_exp_f32_e32 v39, v39
	v_mov_b32_e32 v61, v62
	v_cndmask_b32_e64 v58, 0, v39, s[26:27]
	v_mov_b32_e32 v39, v93
	v_pk_add_f32 v[38:39], v[38:39], v[72:73] neg_lo:[0,1] neg_hi:[0,1]
	s_nop 0
	v_add_f32_e32 v38, v38, v39
	v_mul_f32_e32 v38, 0x3fb8aa3b, v38
	v_exp_f32_e32 v38, v38
	s_nop 0
	v_cndmask_b32_e64 v73, 0, v38, s[24:25]
	v_mov_b32_e32 v38, v37
	v_pk_add_f32 v[38:39], v[38:39], v[70:71] neg_lo:[0,1] neg_hi:[0,1]
	s_nop 0
	v_add_f32_e32 v37, v38, v39
	v_mul_f32_e32 v37, 0x3fb8aa3b, v37
	v_exp_f32_e32 v37, v37
	s_nop 0
	v_cndmask_b32_e64 v38, 0, v37, s[22:23]
	v_mov_b32_e32 v37, v39
	v_pk_add_f32 v[36:37], v[36:37], v[68:69] neg_lo:[0,1] neg_hi:[0,1]
	s_nop 0
	v_add_f32_e32 v36, v36, v37
	v_mul_f32_e32 v36, 0x3fb8aa3b, v36
	v_exp_f32_e32 v36, v36
	s_nop 0
	v_cndmask_b32_e64 v39, 0, v36, s[20:21]
	v_mov_b32_e32 v36, v35
	v_pk_add_f32 v[36:37], v[36:37], v[66:67] neg_lo:[0,1] neg_hi:[0,1]
	s_nop 0
	v_add_f32_e32 v35, v36, v37
	v_mul_f32_e32 v35, 0x3fb8aa3b, v35
	v_exp_f32_e32 v35, v35
	s_nop 0
	v_cndmask_b32_e64 v36, 0, v35, s[18:19]
	v_mov_b32_e32 v35, v37
	v_pk_add_f32 v[34:35], v[34:35], v[64:65] neg_lo:[0,1] neg_hi:[0,1]
	s_nop 0
	v_add_f32_e32 v34, v34, v35
	v_mul_f32_e32 v34, 0x3fb8aa3b, v34
	v_exp_f32_e32 v34, v34
	s_nop 0
	v_cndmask_b32_e64 v37, 0, v34, s[16:17]
	v_mov_b32_e32 v34, v33
	v_pk_add_f32 v[34:35], v[34:35], v[62:63] neg_lo:[0,1] neg_hi:[0,1]
	s_nop 0
	v_add_f32_e32 v33, v34, v35
	v_mul_f32_e32 v33, 0x3fb8aa3b, v33
	v_exp_f32_e32 v33, v33
	s_nop 0
	v_cndmask_b32_e64 v34, 0, v33, s[14:15]
	v_mov_b32_e32 v33, v35
	v_pk_add_f32 v[32:33], v[32:33], v[60:61] neg_lo:[0,1] neg_hi:[0,1]
	v_cvt_pk_bf16_f32 v35, v73, v58
	v_add_f32_e32 v32, v32, v33
	v_mul_f32_e32 v32, 0x3fb8aa3b, v32
	v_exp_f32_e32 v32, v32
	v_cvt_pk_bf16_f32 v33, v37, v36
	ds_bpermute_b32 v60, v53, v94
	s_mov_b32 s14, 0xc2d00000
	v_cndmask_b32_e32 v32, 0, v32, vcc
	v_cvt_pk_bf16_f32 v32, v32, v34
	v_cvt_pk_bf16_f32 v34, v39, v38
	ds_write_b128 v55, v[32:35]
	s_waitcnt lgkmcnt(0)
	s_barrier
	ds_read_b128 v[96:99], v76
	ds_read_b64_tr_b16 v[104:105], v86 offset:34816
	ds_read_b64_tr_b16 v[106:107], v86 offset:35904
	ds_read_b64_tr_b16 v[108:109], v86 offset:34848
	ds_read_b64_tr_b16 v[110:111], v86 offset:35936
	ds_read_b64_tr_b16 v[112:113], v86 offset:34880
	ds_read_b64_tr_b16 v[114:115], v86 offset:35968
	ds_read_b64_tr_b16 v[116:117], v86 offset:34912
	ds_read_b64_tr_b16 v[118:119], v86 offset:36000
	ds_read_b128 v[100:103], v76 offset:64
	ds_read_b64_tr_b16 v[120:121], v86 offset:43520
	ds_read_b64_tr_b16 v[122:123], v86 offset:44608
	ds_read_b64_tr_b16 v[124:125], v86 offset:43552
	ds_read_b64_tr_b16 v[126:127], v86 offset:44640
	ds_read_b64_tr_b16 v[128:129], v86 offset:43584
	ds_read_b64_tr_b16 v[130:131], v86 offset:44672
	ds_read_b64_tr_b16 v[132:133], v86 offset:43616
	ds_read_b64_tr_b16 v[134:135], v86 offset:44704
	v_sub_f32_e32 v59, v59, v60
	v_cmp_lt_f32_e32 vcc, s14, v59
	s_waitcnt lgkmcnt(15)
	v_mfma_f32_16x16x32_bf16 v[16:19], v[96:99], v[104:107], v[16:19]
	s_waitcnt lgkmcnt(13)
	v_mfma_f32_16x16x32_bf16 v[20:23], v[96:99], v[108:111], v[20:23]
	s_waitcnt lgkmcnt(11)
	v_mfma_f32_16x16x32_bf16 v[24:27], v[96:99], v[112:115], v[24:27]
	s_waitcnt lgkmcnt(9)
	v_mfma_f32_16x16x32_bf16 v[28:31], v[96:99], v[116:119], v[28:31]
	s_waitcnt lgkmcnt(6)
	v_mfma_f32_16x16x32_bf16 v[16:19], v[100:103], v[120:123], v[16:19]
	s_waitcnt lgkmcnt(4)
	v_mfma_f32_16x16x32_bf16 v[20:23], v[100:103], v[124:127], v[20:23]
	s_waitcnt lgkmcnt(2)
	v_mfma_f32_16x16x32_bf16 v[24:27], v[100:103], v[128:131], v[24:27]
	s_waitcnt lgkmcnt(0)
	v_mfma_f32_16x16x32_bf16 v[28:31], v[100:103], v[132:135], v[28:31]
	s_cmp_lg_u64 vcc, 0
	s_cselect_b32 s16, 1, 0
	v_mov_b32_e32 v32, s16
	s_andn2_b64 vcc, exec, s[94:95]
	s_cbranch_vccnz .LBB0_310
	s_and_saveexec_b64 s[14:15], s[4:5]
	v_mov_b32_e32 v32, s16
	ds_write_b32 v213, v32
	s_or_b64 exec, exec, s[14:15]
	s_waitcnt lgkmcnt(0)
	s_barrier
	s_and_saveexec_b64 s[14:15], s[98:99]
	s_cbranch_execz .LBB0_309
	v_mbcnt_lo_u32_b32 v32, exec_lo, 0
	v_mbcnt_hi_u32_b32 v32, exec_hi, v32
	v_cmp_eq_u32_e32 vcc, 0, v32
	s_and_b64 exec, exec, vcc
	s_cbranch_execz .LBB0_309
	v_mov_b32_e32 v32, s16
	ds_or_b32 v213, v32
	s_branch .LBB0_309

; __device__ __forceinline__ uint4 ldg16(const void* p) { const u32x4 v = *(const __attribute__((address_space(1))) u32x4*)(p); return make_uint4(v.x, v.y, v.z, v.w); }
; __device__ __forceinline__ void attn_phase(const Params& p, char* shmc, int tid, int wv) {
;     ...
;       {
;         *(uint4*)&Ks[krow * 136 + kc0] = ka;
;         *(uint4*)&Ks[krow * 136 + kc0 + 8] = kb4;
;         const unsigned vw[8] = {va.x, va.y, va.z, va.w, vb.x, vb.y, vb.z, vb.w};
; #pragma unroll
;         for (int i = 0; i < 8; ++i) { Vt[(vd0 + 2 * i) * 72 + vkey] = (u16)(vw[i] & 0xffffu); Vt[(vd0 + 2 * i + 1) * 72 + vkey] = (u16)(vw[i] >> 16); }
;       }
;       __syncthreads();
;       {
;         const int kn = kb > 0 ? kb - 1 : 0;
;         const u16* src = QKV + ((long)kn * 64 + krow) * 6144 + 2048 + h * 128 + kc0;
;         ka = ldg16(src); kb4 = ldg16(src + 8);
;         const u16* vs = QKV + ((long)kn * 64 + vkey) * 6144 + 4096 + h * 128 + vd0;
;         va = ldg16(vs); vb = ldg16(vs + 8);
;       }
;       {
;         const int ntb = (wv >> 2) * 2;
;         f32x4 z[2] = {{0.f, 0.f, 0.f, 0.f}, {0.f, 0.f, 0.f, 0.f}};
; #pragma unroll
;         for (int kk = 0; kk < 4; ++kk) {
;           const bf16x8 a = *(const bf16x8*)&Qs[(16 * mt + r) * 136 + kk * 32 + quad * 8];
; #pragma unroll
;           for (int i = 0; i < 2; ++i) {
;             const bf16x8 b = *(const bf16x8*)&Ks[(16 * (ntb + i) + r) * 136 + kk * 32 + quad * 8];
;             z[i] = __builtin_amdgcn_mfma_f32_16x16x32_bf16(a, b, z[i], 0, 0, 0);
;           }
;         }
; #pragma unroll
;         for (int i = 0; i < 2; ++i)
; #pragma unroll
;           for (int j = 0; j < 4; ++j) Zs[(16 * mt + 4 * quad + j) * 68 + 16 * (ntb + i) + r] = z[i][j] * 0.08838834764831845f;
;       }
;       __syncthreads();
;       {
;         const int row = tid >> 3, part = tid & 7;
;         const float4 za = *(const float4*)&Zs[row * 68 + part * 8], zb = *(const float4*)&Zs[row * 68 + part * 8 + 4];
;         const float z[8] = {za.x, za.y, za.z, za.w, zb.x, zb.y, zb.z, zb.w};
;         const int qpos = qb * 64 + row, kpos0 = kb * 64 + part * 8;
;         float sp[8];
;         float ptot = 0.f;
; #pragma unroll
;         for (int i = 0; i < 8; ++i) {
;           const bool valid = (kpos0 + i) < qpos;
;           sp[i] = valid ? (fmaxf(z[i], 0.f) + __logf(1.f + __expf(-fabsf(z[i])))) : 0.f;
.Lat_bodyB:
	v_sub_u32_e64 v212, s68, 2 clamp
	s_waitcnt vmcnt(5)
	ds_write_b128 v43, v[152:155] offset:17408
	s_waitcnt vmcnt(4)
	ds_write_b128 v43, v[156:159] offset:17424
	ds_write_b128 v77, v[148:151] offset:34816
	ds_write_b128 v77, v[144:147] offset:34832
	v_lshlrev_b64 v[144:145], 6, v[212:213]
	v_lshl_add_u64 v[146:147], v[144:145], 0, v[44:45]
	v_mad_u64_u32 v[148:149], s[14:15], v146, s71, v[40:41]
	v_mad_i32_i24 v149, v147, s71, v149
	s_lshl_b32 s88, s59, 1
	v_lshl_add_u64 v[146:147], v[148:149], 0, s[88:89]
	v_lshl_add_u64 v[146:147], v[146:147], 0, v[56:57]
	v_lshl_add_u64 v[148:149], v[146:147], 0, s[54:55]
	v_add_co_u32_e32 v146, vcc, s66, v146
	v_or_b32_e32 v144, v144, v42
	s_nop 0
	v_addc_co_u32_e32 v147, vcc, 0, v147, vcc
	s_waitcnt lgkmcnt(0)
	s_barrier
	global_load_dwordx4 v[152:155], v[146:147], off
	global_load_dwordx4 v[156:159], v[148:149], off offset:16
	v_mad_u64_u32 v[146:147], s[14:15], v144, s71, v[40:41]
	v_mad_u32_u24 v147, v145, s71, v147
	v_lshl_add_u64 v[144:145], v[146:147], 0, s[88:89]
	v_lshl_add_u64 v[144:145], v[144:145], 0, s[36:37]
	v_lshl_add_u64 v[146:147], v[144:145], 0, s[46:47]
	v_add_co_u32_e32 v144, vcc, s67, v144
	v_add_u32_e32 v58, 0xd000, v84
	s_nop 0
	v_addc_co_u32_e32 v145, vcc, 0, v145, vcc
	global_load_dwordx4 v[148:151], v[144:145], off
	s_nop 0
	global_load_dwordx4 v[144:147], v[146:147], off offset:16
	ds_read_b128 v[96:99], v47
	ds_read_b128 v[112:115], v82 offset:17408
	ds_read_b128 v[128:131], v83 offset:17408
	ds_read_b128 v[100:103], v47 offset:64
	ds_read_b128 v[116:119], v82 offset:17472
	ds_read_b128 v[132:135], v83 offset:17472
	ds_read_b128 v[104:107], v47 offset:128
	ds_read_b128 v[120:123], v82 offset:17536
	ds_read_b128 v[136:139], v83 offset:17536
	ds_read_b128 v[108:111], v47 offset:192
	ds_read_b128 v[124:127], v82 offset:17600
	ds_read_b128 v[140:143], v83 offset:17600
	s_waitcnt lgkmcnt(10)
	v_mfma_f32_16x16x32_bf16 v[36:39], v[96:99], v[112:115], 0
	s_waitcnt lgkmcnt(9)
	v_mfma_f32_16x16x32_bf16 v[32:35], v[96:99], v[128:131], 0
	s_waitcnt lgkmcnt(7)
	v_mfma_f32_16x16x32_bf16 v[36:39], v[100:103], v[116:119], v[36:39]
	s_waitcnt lgkmcnt(6)
	v_mfma_f32_16x16x32_bf16 v[32:35], v[100:103], v[132:135], v[32:35]
	s_waitcnt lgkmcnt(4)
	v_mfma_f32_16x16x32_bf16 v[36:39], v[104:107], v[120:123], v[36:39]
	s_waitcnt lgkmcnt(3)
	v_mfma_f32_16x16x32_bf16 v[32:35], v[104:107], v[136:139], v[32:35]
	s_waitcnt lgkmcnt(1)
	v_mfma_f32_16x16x32_bf16 v[36:39], v[108:111], v[124:127], v[36:39]
	s_waitcnt lgkmcnt(0)
	v_mfma_f32_16x16x32_bf16 v[32:35], v[108:111], v[140:143], v[32:35]
	s_nop 7
	v_mul_f32_e32 v36, 0x3db504f3, v36
	v_mul_f32_e32 v37, 0x3db504f3, v37
	ds_write2_b32 v58, v36, v37 offset1:68
	v_mul_f32_e32 v36, 0x3db504f3, v38
	v_mul_f32_e32 v37, 0x3db504f3, v39
	ds_write2_b32 v58, v36, v37 offset0:136 offset1:204
	v_mul_f32_e32 v32, 0x3db504f3, v32
	v_mul_f32_e32 v33, 0x3db504f3, v33
	v_add_u32_e32 v36, 0xd000, v85
	ds_write2_b32 v36, v32, v33 offset1:68
	v_mul_f32_e32 v32, 0x3db504f3, v34
	v_mul_f32_e32 v33, 0x3db504f3, v35
	ds_write2_b32 v36, v32, v33 offset0:136 offset1:204
	s_waitcnt lgkmcnt(0)
	s_barrier
	ds_read_b128 v[32:35], v51 offset:53248
	ds_read_b128 v[36:39], v51 offset:53264
	v_add_u32_e32 v58, -7, v91
	v_cmp_lt_i32_e32 vcc, v58, v90
	v_add_u32_e32 v58, -6, v91
	v_cmp_lt_i32_e64 s[14:15], v58, v90
	v_add_u32_e32 v58, -5, v91
	v_cmp_lt_i32_e64 s[16:17], v58, v90
	v_add_u32_e32 v58, -4, v91
	v_cmp_lt_i32_e64 s[18:19], v58, v90
	v_add_u32_e32 v58, -3, v91
	v_cmp_lt_i32_e64 s[20:21], v58, v90
	v_add_u32_e32 v58, -2, v91
	v_cmp_lt_i32_e64 s[22:23], v58, v90
	v_add_u32_e32 v58, -1, v91
	v_cmp_lt_i32_e64 s[24:25], v58, v90
	v_cmp_lt_i32_e64 s[26:27], v91, v90
	s_waitcnt lgkmcnt(0)
	v_mul_f32_e64 v96, |v32|, s74
	v_mul_f32_e64 v97, |v33|, s74
	v_mul_f32_e64 v98, |v34|, s74
	v_mul_f32_e64 v99, |v35|, s74
	v_mul_f32_e64 v100, |v36|, s74
	v_mul_f32_e64 v101, |v37|, s74
	v_mul_f32_e64 v102, |v38|, s74
	v_mul_f32_e64 v103, |v39|, s74
	v_exp_f32_e32 v96, v96
	v_exp_f32_e32 v97, v97
	v_exp_f32_e32 v98, v98
	v_exp_f32_e32 v99, v99
	v_exp_f32_e32 v100, v100
	v_exp_f32_e32 v101, v101
	v_exp_f32_e32 v102, v102
	v_exp_f32_e32 v103, v103
	v_max_f32_e32 v60, v32, v32
	v_max_f32_e32 v62, v33, v33
	v_max_f32_e32 v64, v34, v34
	v_max_f32_e32 v66, v35, v35
	v_max_f32_e32 v68, v36, v36
	v_max_f32_e32 v70, v37, v37
	v_max_f32_e32 v72, v38, v38
	v_max_f32_e32 v74, v39, v39
	v_add_f32_e32 v96, 1.0, v96
	v_add_f32_e32 v97, 1.0, v97
	v_add_f32_e32 v98, 1.0, v98
	v_add_f32_e32 v99, 1.0, v99
	v_add_f32_e32 v100, 1.0, v100
	v_add_f32_e32 v101, 1.0, v101
	v_add_f32_e32 v102, 1.0, v102
	v_add_f32_e32 v103, 1.0, v103
	v_log_f32_e32 v96, v96
	v_log_f32_e32 v97, v97
	v_log_f32_e32 v98, v98
	v_log_f32_e32 v99, v99
	v_log_f32_e32 v100, v100
	v_log_f32_e32 v101, v101
	v_log_f32_e32 v102, v102
	v_log_f32_e32 v103, v103
	v_max_f32_e32 v60, 0, v60
	v_max_f32_e32 v62, 0, v62
	v_max_f32_e32 v64, 0, v64
	v_max_f32_e32 v66, 0, v66
	v_max_f32_e32 v68, 0, v68
	v_max_f32_e32 v70, 0, v70
	v_max_f32_e32 v72, 0, v72
	v_max_f32_e32 v74, 0, v74
	v_mul_f32_e32 v104, 0x3f317217, v96
	v_mul_f32_e32 v105, 0x3f317217, v97
	v_mul_f32_e32 v106, 0x3f317217, v98
	v_mul_f32_e32 v107, 0x3f317217, v99
	v_mul_f32_e32 v108, 0x3f317217, v100
	v_mul_f32_e32 v109, 0x3f317217, v101
	v_mul_f32_e32 v110, 0x3f317217, v102
	v_mul_f32_e32 v111, 0x3f317217, v103
	v_fma_f32 v104, v96, s75, -v104
	v_fma_f32 v105, v97, s75, -v105
	v_fma_f32 v106, v98, s75, -v106
	v_fma_f32 v107, v99, s75, -v107
	v_fma_f32 v108, v100, s75, -v108
	v_fma_f32 v109, v101, s75, -v109
	v_fma_f32 v110, v102, s75, -v110
	v_fma_f32 v111, v103, s75, -v111
; __device__ __forceinline__ unsigned pack2(float a, float b) { const f32v2_ v = {a, b}; const bf16v2_ r = __builtin_convertvector(v, bf16v2_); return __builtin_bit_cast(unsigned, r); }
; __device__ __forceinline__ float shfl_idx(float v, int srclane) { return __int_as_float(__builtin_amdgcn_ds_bpermute(srclane << 2, __float_as_int(v))); }
; __device__ __forceinline__ void attn_phase(const Params& p, char* shmc, int tid, int wv) {
;     ...
;       {
;         const int row = tid >> 3, part = tid & 7;
;         const float4 za = *(const float4*)&Zs[row * 68 + part * 8], zb = *(const float4*)&Zs[row * 68 + part * 8 + 4];
;         const float z[8] = {za.x, za.y, za.z, za.w, zb.x, zb.y, zb.z, zb.w};
;         const int qpos = qb * 64 + row, kpos0 = kb * 64 + part * 8;
;         float sp[8];
;         float ptot = 0.f;
; #pragma unroll
;         for (int i = 0; i < 8; ++i) {
;           const bool valid = (kpos0 + i) < qpos;
;           sp[i] = valid ? (fmaxf(z[i], 0.f) + __logf(1.f + __expf(-fabsf(z[i])))) : 0.f;
;           ptot += sp[i];
;         }
;         float tot = ptot;
; #pragma unroll
;         for (int o = 1; o < 8; o <<= 1) { const float v = shfl_idx(tot, lane + o); if (part + o < 8) tot += v; }
;         float running = carry - (tot - ptot);
;         float a[8];
; #pragma unroll
;         for (int i = 7; i >= 0; --i) {
;           const bool valid = (kpos0 + i) < qpos;
;           a[i] = valid ? __expf(z[i] - sp[i] + running) : 0.f;
;           running -= sp[i];
;         }
;         const float all = shfl_idx(tot, lane & ~7);
;         carry -= all;
;         *(uint4*)&Ps[row * 72 + part * 8] = make_uint4(pack2(a[0], a[1]), pack2(a[2], a[3]), pack2(a[4], a[5]), pack2(a[6], a[7]));
;       }
;       __syncthreads();
;       {
;         const int ntb = (wv >> 2) * 4;
; #pragma unroll
;         for (int kk = 0; kk < 2; ++kk) {
;           const bf16x8 a = *(const bf16x8*)&Ps[(16 * mt + r) * 72 + kk * 32 + quad * 8];
; #pragma unroll
;           for (int i = 0; i < 4; ++i) {
;             const bf16x8 b = *(const bf16x8*)&Vt[(16 * (ntb + i) + r) * 72 + kk * 32 + quad * 8];
;             oacc[i] = __builtin_amdgcn_mfma_f32_16x16x32_bf16(a, b, oacc[i], 0, 0, 0);
;           }
;         }
;       }
;       const int more = __syncthreads_or(carry > -120.f);
;       if (!more) break;
	v_fmac_f32_e32 v104, 0x3377d1cf, v96
	v_fmac_f32_e32 v105, 0x3377d1cf, v97
	v_fmac_f32_e32 v106, 0x3377d1cf, v98
	v_fmac_f32_e32 v107, 0x3377d1cf, v99
	v_fmac_f32_e32 v108, 0x3377d1cf, v100
	v_fmac_f32_e32 v109, 0x3377d1cf, v101
	v_fmac_f32_e32 v110, 0x3377d1cf, v102
	v_fmac_f32_e32 v111, 0x3377d1cf, v103
	v_fmac_f32_e32 v104, 0x3f317217, v96
	v_fmac_f32_e32 v105, 0x3f317217, v97
	v_fmac_f32_e32 v106, 0x3f317217, v98
	v_fmac_f32_e32 v107, 0x3f317217, v99
	v_fmac_f32_e32 v108, 0x3f317217, v100
	v_fmac_f32_e32 v109, 0x3f317217, v101
	v_fmac_f32_e32 v110, 0x3f317217, v102
	v_fmac_f32_e32 v111, 0x3f317217, v103
	v_add_f32_e32 v60, v60, v104
	v_add_f32_e32 v62, v62, v105
	v_add_f32_e32 v64, v64, v106
	v_add_f32_e32 v66, v66, v107
	v_add_f32_e32 v68, v68, v108
	v_add_f32_e32 v70, v70, v109
	v_add_f32_e32 v72, v72, v110
	v_add_f32_e32 v74, v74, v111
	v_cndmask_b32_e32 v60, 0, v60, vcc
	v_cndmask_b32_e64 v62, 0, v62, s[14:15]
	v_cndmask_b32_e64 v64, 0, v64, s[16:17]
	v_cndmask_b32_e64 v66, 0, v66, s[18:19]
	v_cndmask_b32_e64 v68, 0, v68, s[20:21]
	v_cndmask_b32_e64 v70, 0, v70, s[22:23]
	v_cndmask_b32_e64 v72, 0, v72, s[24:25]
	v_cndmask_b32_e64 v74, 0, v74, s[26:27]
	v_add_f32_e32 v58, 0, v60
	v_add_f32_e32 v58, v58, v62
	v_add_f32_e32 v58, v58, v64
	v_add_f32_e32 v58, v58, v66
	v_add_f32_e32 v58, v58, v68
	v_add_f32_e32 v58, v58, v70
	v_add_f32_e32 v58, v58, v72
	v_add_f32_e32 v58, v58, v74
	ds_bpermute_b32 v61, v78, v58
	v_mov_b32_e32 v73, v74
	v_mov_b32_e32 v71, v72
	v_mov_b32_e32 v69, v70
	v_mov_b32_e32 v67, v68
	s_waitcnt lgkmcnt(0)
	v_add_f32_e32 v61, v58, v61
	v_cndmask_b32_e64 v61, v61, v58, s[8:9]
	ds_bpermute_b32 v63, v79, v61
	v_mov_b32_e32 v65, v66
	s_bitcmp1_b32 exec_hi, 0
	s_waitcnt lgkmcnt(0)
	v_add_f32_e32 v63, v61, v63
	v_cndmask_b32_e64 v61, v61, v63, s[10:11]
	ds_bpermute_b32 v63, v80, v61
	s_waitcnt lgkmcnt(0)
	v_add_f32_e32 v63, v61, v63
	v_cndmask_b32_e64 v94, v61, v63, s[12:13]
	v_sub_f32_e32 v75, v94, v58
	v_mov_b32_e32 v58, v39
	v_pk_add_f32 v[92:93], v[58:59], v[74:75] neg_lo:[0,1] neg_hi:[0,1]
	v_mov_b32_e32 v63, v64
	v_add_f32_e32 v39, v92, v93
	v_mul_f32_e32 v39, 0x3fb8aa3b, v39
	v_exp_f32_e32 v39, v39
	v_mov_b32_e32 v61, v62
	v_cndmask_b32_e64 v58, 0, v39, s[26:27]
	v_mov_b32_e32 v39, v93
	v_pk_add_f32 v[38:39], v[38:39], v[72:73] neg_lo:[0,1] neg_hi:[0,1]
	s_nop 0
	v_add_f32_e32 v38, v38, v39
	v_mul_f32_e32 v38, 0x3fb8aa3b, v38
	v_exp_f32_e32 v38, v38
	s_nop 0
	v_cndmask_b32_e64 v73, 0, v38, s[24:25]
	v_mov_b32_e32 v38, v37
	v_pk_add_f32 v[38:39], v[38:39], v[70:71] neg_lo:[0,1] neg_hi:[0,1]
	s_nop 0
	v_add_f32_e32 v37, v38, v39
	v_mul_f32_e32 v37, 0x3fb8aa3b, v37
	v_exp_f32_e32 v37, v37
	s_nop 0
	v_cndmask_b32_e64 v38, 0, v37, s[22:23]
	v_mov_b32_e32 v37, v39
	v_pk_add_f32 v[36:37], v[36:37], v[68:69] neg_lo:[0,1] neg_hi:[0,1]
	s_nop 0
	v_add_f32_e32 v36, v36, v37
	v_mul_f32_e32 v36, 0x3fb8aa3b, v36
	v_exp_f32_e32 v36, v36
	s_nop 0
	v_cndmask_b32_e64 v39, 0, v36, s[20:21]
	v_mov_b32_e32 v36, v35
	v_pk_add_f32 v[36:37], v[36:37], v[66:67] neg_lo:[0,1] neg_hi:[0,1]
	s_nop 0
	v_add_f32_e32 v35, v36, v37
	v_mul_f32_e32 v35, 0x3fb8aa3b, v35
	v_exp_f32_e32 v35, v35
	s_nop 0
	v_cndmask_b32_e64 v36, 0, v35, s[18:19]
	v_mov_b32_e32 v35, v37
	v_pk_add_f32 v[34:35], v[34:35], v[64:65] neg_lo:[0,1] neg_hi:[0,1]
	s_nop 0
	v_add_f32_e32 v34, v34, v35
	v_mul_f32_e32 v34, 0x3fb8aa3b, v34
	v_exp_f32_e32 v34, v34
	s_nop 0
	v_cndmask_b32_e64 v37, 0, v34, s[16:17]
	v_mov_b32_e32 v34, v33
	v_pk_add_f32 v[34:35], v[34:35], v[62:63] neg_lo:[0,1] neg_hi:[0,1]
	s_nop 0
	v_add_f32_e32 v33, v34, v35
	v_mul_f32_e32 v33, 0x3fb8aa3b, v33
	v_exp_f32_e32 v33, v33
	s_nop 0
	v_cndmask_b32_e64 v34, 0, v33, s[14:15]
	v_mov_b32_e32 v33, v35
	v_pk_add_f32 v[32:33], v[32:33], v[60:61] neg_lo:[0,1] neg_hi:[0,1]
	v_cvt_pk_bf16_f32 v35, v73, v58
	v_add_f32_e32 v32, v32, v33
	v_mul_f32_e32 v32, 0x3fb8aa3b, v32
	v_exp_f32_e32 v32, v32
	v_cvt_pk_bf16_f32 v33, v37, v36
	ds_bpermute_b32 v60, v53, v94
	s_mov_b32 s14, 0xc2d00000
	v_cndmask_b32_e32 v32, 0, v32, vcc
	v_cvt_pk_bf16_f32 v32, v32, v34
	v_cvt_pk_bf16_f32 v34, v39, v38
	ds_write_b128 v55, v[32:35]
	s_waitcnt lgkmcnt(0)
	s_barrier
	ds_read_b128 v[96:99], v76
	ds_read_b64_tr_b16 v[104:105], v86 offset:34816
	ds_read_b64_tr_b16 v[106:107], v86 offset:35904
	ds_read_b64_tr_b16 v[108:109], v86 offset:34848
	ds_read_b64_tr_b16 v[110:111], v86 offset:35936
	ds_read_b64_tr_b16 v[112:113], v86 offset:34880
	ds_read_b64_tr_b16 v[114:115], v86 offset:35968
	ds_read_b64_tr_b16 v[116:117], v86 offset:34912
	ds_read_b64_tr_b16 v[118:119], v86 offset:36000
	ds_read_b128 v[100:103], v76 offset:64
	ds_read_b64_tr_b16 v[120:121], v86 offset:43520
	ds_read_b64_tr_b16 v[122:123], v86 offset:44608
	ds_read_b64_tr_b16 v[124:125], v86 offset:43552
	ds_read_b64_tr_b16 v[126:127], v86 offset:44640
	ds_read_b64_tr_b16 v[128:129], v86 offset:43584
	ds_read_b64_tr_b16 v[130:131], v86 offset:44672
	ds_read_b64_tr_b16 v[132:133], v86 offset:43616
	ds_read_b64_tr_b16 v[134:135], v86 offset:44704
	v_sub_f32_e32 v59, v59, v60
	v_cmp_lt_f32_e32 vcc, s14, v59
	s_waitcnt lgkmcnt(15)
	v_mfma_f32_16x16x32_bf16 v[16:19], v[96:99], v[104:107], v[16:19]
	s_waitcnt lgkmcnt(13)
	v_mfma_f32_16x16x32_bf16 v[20:23], v[96:99], v[108:111], v[20:23]
	s_waitcnt lgkmcnt(11)
	v_mfma_f32_16x16x32_bf16 v[24:27], v[96:99], v[112:115], v[24:27]
	s_waitcnt lgkmcnt(9)
	v_mfma_f32_16x16x32_bf16 v[28:31], v[96:99], v[116:119], v[28:31]
	s_waitcnt lgkmcnt(6)
	v_mfma_f32_16x16x32_bf16 v[16:19], v[100:103], v[120:123], v[16:19]
	s_waitcnt lgkmcnt(4)
	v_mfma_f32_16x16x32_bf16 v[20:23], v[100:103], v[124:127], v[20:23]
	s_waitcnt lgkmcnt(2)
	v_mfma_f32_16x16x32_bf16 v[24:27], v[100:103], v[128:131], v[24:27]
	s_waitcnt lgkmcnt(0)
	v_mfma_f32_16x16x32_bf16 v[28:31], v[100:103], v[132:135], v[28:31]
	s_cmp_lg_u64 vcc, 0
	s_cselect_b32 s16, 1, 0
	v_mov_b32_e32 v32, s16
	s_andn2_b64 vcc, exec, s[94:95]
	s_cbranch_vccnz .Lat_310B
	s_and_saveexec_b64 s[14:15], s[4:5]
	v_mov_b32_e32 v32, s16
	ds_write_b32 v213, v32
	s_or_b64 exec, exec, s[14:15]
	s_waitcnt lgkmcnt(0)
	s_barrier
	s_and_saveexec_b64 s[14:15], s[98:99]
	s_cbranch_execz .Lat_309B
	v_mbcnt_lo_u32_b32 v32, exec_lo, 0
	v_mbcnt_hi_u32_b32 v32, exec_hi, v32
	v_cmp_eq_u32_e32 vcc, 0, v32
	s_and_b64 exec, exec, vcc
	s_cbranch_execz .Lat_309B
	v_mov_b32_e32 v32, s16
	ds_or_b32 v213, v32
	s_branch .Lat_309B
